# phase B rebalanced: 10240 (was 5632) weight-conversion tiles before the mid barrier, since the recurrence chain is faster now
# baseline (speedup 1.0000x reference)
; __device__ void phaseB(const Params& p, char* smem) {
;     ...
;     constexpr int NCV = NEXP * 2 * 128, NCV1 = 5632;
;     u16* T = (u16*)smem;
;     const int tr = threadIdx.x >> 4, tc4 = (threadIdx.x & 15) * 4;
;     auto cload = [&](int u, float4 (&v)[4]) {
;       const int tile = u & 127, mat = (u >> 7) & 1, e = u >> 8;
;       const float* W = (mat ? p.w_up : p.w_gate) + (size_t)e * DM * DEXP + (size_t)((tile & 15) * 64) * DEXP + (tile >> 4) * 64;
; #pragma unroll
;       for (int i = 0; i < 4; i++) v[i] = *(const float4*)&W[(size_t)(tr + 16 * i) * DEXP + tc4];
;     };
;     auto cproc = [&](int u, float4 (&v)[4]) {
;       const int tile = u & 127, mat = (u >> 7) & 1, e = u >> 8;
;       u16* WT = (mat ? p.WuT : p.WgT) + (size_t)e * DEXP * DM;
;       const int k0 = (tile & 15) * 64, n0 = (tile >> 4) * 64;
;       __syncthreads();
; #pragma unroll
;       for (int i = 0; i < 4; i++) {
;         const int k = tr + 16 * i;
;         T[(tc4 + 0) * 72 + k] = f2bf(v[i].x); T[(tc4 + 1) * 72 + k] = f2bf(v[i].y);
;         T[(tc4 + 2) * 72 + k] = f2bf(v[i].z); T[(tc4 + 3) * 72 + k] = f2bf(v[i].w);
;       }
;       __syncthreads();
;       const int n = threadIdx.x >> 2, seg = (threadIdx.x & 3) * 16;
;       const u32x4 a = *(const u32x4*)&T[n * 72 + seg], b = *(const u32x4*)&T[n * 72 + seg + 8];
;       *(u32x4*)&WT[(size_t)(n0 + n) * DM + k0 + seg] = a;
;       *(u32x4*)&WT[(size_t)(n0 + n) * DM + k0 + seg + 8] = b;
;     };
;     auto conv_range = [&](int u, int uend) -> int {
;       float4 va[4], vb[4];
;       if (u < uend) cload(u, va);
;       while (u < uend) {
;         if (u + nb < uend) cload(u + nb, vb);
;         cproc(u, va);
;         u += nb;
;         if (u >= uend) break;
;         if (u + nb < uend) cload(u + nb, va);
;         cproc(u, vb);
;         u += nb;
;       }
;       return u;
;     };
.LBB0_825:
	v_and_b32_e32 v96, 60, v127
	s_cmpk_gt_i32 s4, 0x27ff
	v_lshlrev_b32_e32 v98, 11, v132
	v_lshlrev_b32_e32 v100, 2, v96
	v_and_b32_e32 v97, 48, v140
	v_lshlrev_b32_e32 v137, 1, v132
	s_cbranch_scc1 .LBB0_836
	s_ashr_i32 s0, s4, 8
	v_readlane_b32 s8, v240, 26
	s_bitcmp0_b32 s4, 7
	v_readlane_b32 s16, v240, 34
	v_readlane_b32 s17, v240, 35
	v_readlane_b32 s18, v240, 36
	v_readlane_b32 s19, v240, 37
	s_cselect_b32 s2, s17, s19
	s_cselect_b32 s3, s16, s18
	s_ashr_i32 s1, s0, 31
	s_lshl_b64 s[0:1], s[0:1], 21
	s_add_u32 s0, s3, s0
	v_readlane_b32 s9, v240, 27
	s_addc_u32 s1, s2, s1
	s_lshl_b32 s2, s40, 17
	s_lshl_b32 s9, s40, 15
	s_and_b32 s2, s2, 0x1e0000
	s_add_u32 s0, s0, s2
	s_addc_u32 s1, s1, 0
	s_lshl_b32 s2, s4, 4
	s_and_b32 s2, s2, 0x700
	s_add_u32 s0, s0, s2
	s_waitcnt vmcnt(2)
	v_mov_b32_e32 v33, 0
	s_addc_u32 s1, s1, 0
	v_mov_b32_e32 v99, v33
	v_add_u32_e32 v34, 0x8000, v98
	v_mov_b32_e32 v35, v33
	s_waitcnt vmcnt(1)
	v_add_u32_e32 v36, 0x10000, v98
	v_mov_b32_e32 v37, v33
	v_add_u32_e32 v38, 0x18000, v98
	v_mov_b32_e32 v39, v33
	s_waitcnt vmcnt(0)
	v_lshl_add_u64 v[0:1], s[0:1], 0, v[98:99]
	v_mov_b32_e32 v101, v33
	v_lshl_add_u64 v[2:3], s[0:1], 0, v[34:35]
	v_lshl_add_u64 v[8:9], s[0:1], 0, v[36:37]
	v_lshl_add_u64 v[10:11], s[0:1], 0, v[38:39]
	v_lshl_add_u64 v[0:1], v[0:1], 0, v[100:101]
	v_lshl_add_u64 v[4:5], v[2:3], 0, v[100:101]
	v_lshl_add_u64 v[8:9], v[8:9], 0, v[100:101]
	v_lshl_add_u64 v[12:13], v[10:11], 0, v[100:101]
	global_load_dwordx4 v[0:3], v[0:1], off
	s_nop 0
	global_load_dwordx4 v[4:7], v[4:5], off
	s_nop 0
	global_load_dwordx4 v[8:11], v[8:9], off
	s_nop 0
	global_load_dwordx4 v[12:15], v[12:13], off
	v_readlane_b32 s14, v240, 32
	s_lshl_b32 s0, s5, 15
	v_readlane_b32 s10, v240, 28
	v_mul_u32_u24_e32 v16, 0x90, v96
	s_add_i32 s14, s0, s9
	s_add_i32 s0, s5, s24
	v_readlane_b32 s11, v240, 29
	v_readlane_b32 s12, v240, 30
	v_readlane_b32 s13, v240, 31
	v_add3_u32 v40, 0, v16, v137
	v_mul_u32_u24_e32 v16, 0x90, v135
	v_lshlrev_b32_e32 v17, 1, v97
	s_lshl_b32 s3, s40, 2
	s_lshl_b32 s6, s24, 3
	s_lshl_b32 s10, s24, 2
	s_add_i32 s0, s0, s40
	v_add3_u32 v41, 0, v16, v17
	s_lshl_b32 s11, s4, 6
	s_lshl_b32 s2, s24, 7
	s_lshl_b32 s12, s5, 2
	s_lshl_b32 s7, s24, 1
	s_lshl_b32 s8, s24, 16
	s_add_i32 s9, s6, s3
	s_add_i32 s10, s10, s3
	s_lshl_b32 s13, s0, 6
	s_lshl_b32 s5, s24, 15
	v_readlane_b32 s15, v240, 33
	v_readlane_b32 s20, v240, 38
	v_readlane_b32 s21, v240, 39
	v_readlane_b32 s22, v240, 40
	v_readlane_b32 s23, v240, 41
	s_branch .LBB0_828
.LBB0_827:
	v_cvt_pk_bf16_f32 v32, v20, s0
	s_barrier
	ds_write_b16 v40, v32
	v_cvt_pk_bf16_f32 v32, v21, s0
	ds_write_b16 v40, v32 offset:144
	v_cvt_pk_bf16_f32 v32, v22, s0
	ds_write_b16 v40, v32 offset:288
	v_cvt_pk_bf16_f32 v32, v23, s0
	ds_write_b16 v40, v32 offset:432
	v_cvt_pk_bf16_f32 v32, v16, s0
	ds_write_b16 v40, v32 offset:32
	v_cvt_pk_bf16_f32 v32, v17, s0
	ds_write_b16 v40, v32 offset:176
	v_cvt_pk_bf16_f32 v32, v18, s0
	ds_write_b16 v40, v32 offset:320
	v_cvt_pk_bf16_f32 v32, v19, s0
	ds_write_b16 v40, v32 offset:464
	v_cvt_pk_bf16_f32 v32, v28, s0
	ds_write_b16 v40, v32 offset:64
	v_cvt_pk_bf16_f32 v32, v29, s0
	ds_write_b16 v40, v32 offset:208
	v_cvt_pk_bf16_f32 v32, v30, s0
	ds_write_b16 v40, v32 offset:352
	v_cvt_pk_bf16_f32 v32, v31, s0
	ds_write_b16 v40, v32 offset:496
	v_cvt_pk_bf16_f32 v32, v24, s0
	s_add_i32 s4, s25, s24
	ds_write_b16 v40, v32 offset:96
	v_cvt_pk_bf16_f32 v32, v25, s0
	s_bitcmp0_b32 s25, 7
	ds_write_b16 v40, v32 offset:240
	v_cvt_pk_bf16_f32 v32, v26, s0
	s_cselect_b32 s14, s75, s77
	s_cselect_b32 s16, s74, s76
	ds_write_b16 v40, v32 offset:384
	v_cvt_pk_bf16_f32 v32, v27, s0
	s_add_i32 s0, s10, s12
	s_and_b32 s17, s0, 0x1c0
	s_ashr_i32 s0, s25, 8
	ds_write_b16 v40, v32 offset:528
	s_ashr_i32 s1, s0, 31
	s_waitcnt lgkmcnt(0)
	s_barrier
	ds_read_b128 v[42:45], v41
	ds_read_b128 v[46:49], v41 offset:16
	s_and_b32 s18, s13, 0x3c0
	s_lshl_b64 s[0:1], s[0:1], 20
	s_add_u32 s0, s16, s0
	v_add_lshl_u32 v32, s17, v135, 10
	s_addc_u32 s1, s14, s1
	v_or3_b32 v32, v32, s18, v97
	s_add_i32 s11, s11, s2
	s_add_i32 s12, s12, s6
	s_add_i32 s13, s13, s2
	v_lshlrev_b32_e32 v32, 1, v32
	s_cmpk_gt_i32 s4, 0x27ff
	s_waitcnt lgkmcnt(1)
	global_store_dwordx4 v32, v[42:45], s[0:1]
	s_waitcnt lgkmcnt(0)
	global_store_dwordx4 v32, v[46:49], s[0:1] offset:16
	s_cselect_b64 s[0:1], -1, 0
	s_mov_b32 s25, s4
	s_mov_b32 s14, s15
	s_and_b64 vcc, exec, s[0:1]
	s_cbranch_vccnz .LBB0_837
; __device__ void phaseB(const Params& p, char* smem) {
;     ...
;     auto cload = [&](int u, float4 (&v)[4]) {
;       const int tile = u & 127, mat = (u >> 7) & 1, e = u >> 8;
;       const float* W = (mat ? p.w_up : p.w_gate) + (size_t)e * DM * DEXP + (size_t)((tile & 15) * 64) * DEXP + (tile >> 4) * 64;
; #pragma unroll
;       for (int i = 0; i < 4; i++) v[i] = *(const float4*)&W[(size_t)(tr + 16 * i) * DEXP + tc4];
;     };
;     auto cproc = [&](int u, float4 (&v)[4]) {
;       const int tile = u & 127, mat = (u >> 7) & 1, e = u >> 8;
;       u16* WT = (mat ? p.WuT : p.WgT) + (size_t)e * DEXP * DM;
;       const int k0 = (tile & 15) * 64, n0 = (tile >> 4) * 64;
;       __syncthreads();
; #pragma unroll
;       for (int i = 0; i < 4; i++) {
;         const int k = tr + 16 * i;
;         T[(tc4 + 0) * 72 + k] = f2bf(v[i].x); T[(tc4 + 1) * 72 + k] = f2bf(v[i].y);
;         T[(tc4 + 2) * 72 + k] = f2bf(v[i].z); T[(tc4 + 3) * 72 + k] = f2bf(v[i].w);
;       }
;       __syncthreads();
;       const int n = threadIdx.x >> 2, seg = (threadIdx.x & 3) * 16;
;       const u32x4 a = *(const u32x4*)&T[n * 72 + seg], b = *(const u32x4*)&T[n * 72 + seg + 8];
;       *(u32x4*)&WT[(size_t)(n0 + n) * DM + k0 + seg] = a;
;       *(u32x4*)&WT[(size_t)(n0 + n) * DM + k0 + seg + 8] = b;
;     };
;     auto conv_range = [&](int u, int uend) -> int {
;       float4 va[4], vb[4];
;       if (u < uend) cload(u, va);
;       while (u < uend) {
;         if (u + nb < uend) cload(u + nb, vb);
;         cproc(u, va);
;         u += nb;
;         if (u >= uend) break;
;         if (u + nb < uend) cload(u + nb, va);
;         cproc(u, vb);
;         u += nb;
;       }
;       return u;
.LBB0_828:
	s_add_i32 s25, s4, s24
	s_cmpk_lt_i32 s25, 0x2800
	s_cselect_b64 s[0:1], -1, 0
	s_cmpk_gt_i32 s25, 0x27ff
	s_cbranch_scc1 .LBB0_830
	s_ashr_i32 s16, s25, 8
	v_readlane_b32 s36, v240, 26
	s_bitcmp0_b32 s25, 7
	v_readlane_b32 s44, v240, 34
	v_readlane_b32 s45, v240, 35
	v_readlane_b32 s46, v240, 36
	v_readlane_b32 s47, v240, 37
	s_cselect_b32 s15, s45, s47
	s_cselect_b32 s18, s44, s46
	s_ashr_i32 s17, s16, 31
	s_lshl_b64 s[16:17], s[16:17], 21
	s_add_u32 s16, s18, s16
	s_addc_u32 s15, s15, s17
	s_add_i32 s17, s5, s14
	s_and_b32 s17, s17, 0x78000
	s_lshl_b32 s17, s17, 2
	s_add_u32 s16, s16, s17
	s_addc_u32 s15, s15, 0
	s_add_i32 s17, s10, s12
	s_and_b32 s17, s17, 0x1c0
	s_lshl_b32 s17, s17, 2
	s_add_u32 s16, s16, s17
	s_addc_u32 s17, s15, 0
	v_lshl_add_u64 v[16:17], s[16:17], 0, v[98:99]
	v_lshlrev_b32_e32 v32, 2, v96
	v_lshl_add_u64 v[18:19], s[16:17], 0, v[34:35]
	v_lshl_add_u64 v[24:25], s[16:17], 0, v[36:37]
	v_lshl_add_u64 v[26:27], s[16:17], 0, v[38:39]
	v_lshl_add_u64 v[16:17], v[16:17], 0, v[32:33]
	v_lshl_add_u64 v[18:19], v[18:19], 0, v[32:33]
	v_lshl_add_u64 v[24:25], v[24:25], 0, v[32:33]
	v_lshl_add_u64 v[26:27], v[26:27], 0, v[32:33]
	global_load_dwordx4 v[20:23], v[16:17], off
	s_nop 0
	global_load_dwordx4 v[16:19], v[18:19], off
	s_nop 0
	global_load_dwordx4 v[28:31], v[24:25], off
	s_nop 0
	global_load_dwordx4 v[24:27], v[26:27], off
	v_readlane_b32 s37, v240, 27
	v_readlane_b32 s38, v240, 28
	v_readlane_b32 s39, v240, 29
	v_readlane_b32 s40, v240, 30
	v_readlane_b32 s41, v240, 31
	v_readlane_b32 s42, v240, 32
	v_readlane_b32 s43, v240, 33
	v_readlane_b32 s48, v240, 38
	v_readlane_b32 s49, v240, 39
	v_readlane_b32 s50, v240, 40
	v_readlane_b32 s51, v240, 41
.LBB0_830:
	s_waitcnt vmcnt(3)
	v_cvt_pk_bf16_f32 v32, v0, s0
	s_barrier
	ds_write_b16 v40, v32
	v_cvt_pk_bf16_f32 v32, v1, s0
	ds_write_b16 v40, v32 offset:144
	v_cvt_pk_bf16_f32 v32, v2, s0
	ds_write_b16 v40, v32 offset:288
	v_cvt_pk_bf16_f32 v32, v3, s0
	ds_write_b16 v40, v32 offset:432
	s_waitcnt vmcnt(2)
	v_cvt_pk_bf16_f32 v32, v4, s0
	ds_write_b16 v40, v32 offset:32
	v_cvt_pk_bf16_f32 v32, v5, s0
	ds_write_b16 v40, v32 offset:176
	v_cvt_pk_bf16_f32 v32, v6, s0
	ds_write_b16 v40, v32 offset:320
	v_cvt_pk_bf16_f32 v32, v7, s0
	ds_write_b16 v40, v32 offset:464
	s_waitcnt vmcnt(1)
	v_cvt_pk_bf16_f32 v32, v8, s0
	ds_write_b16 v40, v32 offset:64
	v_cvt_pk_bf16_f32 v32, v9, s0
	ds_write_b16 v40, v32 offset:208
	v_cvt_pk_bf16_f32 v32, v10, s0
	ds_write_b16 v40, v32 offset:352
	v_cvt_pk_bf16_f32 v32, v11, s0
	ds_write_b16 v40, v32 offset:496
	s_waitcnt vmcnt(0)
	v_cvt_pk_bf16_f32 v32, v12, s0
	ds_write_b16 v40, v32 offset:96
	v_cvt_pk_bf16_f32 v32, v13, s0
	s_bitcmp0_b32 s4, 7
	ds_write_b16 v40, v32 offset:240
	v_cvt_pk_bf16_f32 v32, v14, s0
	s_cselect_b32 s15, s75, s77
	s_cselect_b32 s18, s74, s76
	ds_write_b16 v40, v32 offset:384
	v_cvt_pk_bf16_f32 v32, v15, s0
	s_add_i32 s16, s3, s12
	ds_write_b16 v40, v32 offset:528
	s_and_b32 s19, s16, 0x1c0
	s_ashr_i32 s16, s4, 8
	s_waitcnt lgkmcnt(0)
	s_barrier
	ds_read_b128 v[42:45], v41
	ds_read_b128 v[46:49], v41 offset:16
	s_ashr_i32 s17, s16, 31
	s_and_b32 s20, s11, 0x3c0
	s_lshl_b64 s[16:17], s[16:17], 20
	v_add_lshl_u32 v32, s19, v135, 10
	s_add_u32 s16, s18, s16
	v_or3_b32 v32, v32, s20, v97
	s_addc_u32 s17, s15, s17
	v_lshlrev_b32_e32 v32, 1, v32
	s_andn2_b64 vcc, exec, s[0:1]
	s_mov_b64 s[0:1], -1
	s_waitcnt lgkmcnt(1)
	global_store_dwordx4 v32, v[42:45], s[16:17]
	s_waitcnt lgkmcnt(0)
	global_store_dwordx4 v32, v[46:49], s[16:17] offset:16
	s_cbranch_vccnz .LBB0_835
	s_add_i32 s4, s7, s4
	s_cmpk_lt_i32 s4, 0x2800
	s_cbranch_scc1 .LBB0_833
	s_add_i32 s15, s14, s8
	s_mov_b64 s[0:1], 0
